# speedup vs baseline: 1.0079x; 1.0079x over previous
.LBB0_133:
	global_load_dword v65, v4, s[12:13]
	global_load_dword v66, v4, s[12:13] offset:4
	global_load_dword v67, v4, s[12:13] offset:8
	global_load_dword v68, v4, s[12:13] offset:12
	global_load_dword v69, v4, s[12:13] offset:16
	global_load_dword v70, v4, s[12:13] offset:20
	global_load_dword v71, v4, s[12:13] offset:24
	global_load_dword v72, v4, s[12:13] offset:28
	global_load_dword v73, v4, s[12:13] offset:32
	global_load_dword v74, v4, s[12:13] offset:36
	global_load_dword v75, v4, s[12:13] offset:40
	global_load_dword v76, v4, s[12:13] offset:44
	global_load_dword v77, v4, s[12:13] offset:48
	global_load_dword v78, v4, s[12:13] offset:52
	global_load_dword v79, v4, s[12:13] offset:56
	global_load_dword v80, v4, s[12:13] offset:60
	global_load_dword v81, v4, s[12:13] offset:64
	global_load_dword v82, v4, s[12:13] offset:68
	global_load_dword v83, v4, s[12:13] offset:72
	global_load_dword v84, v4, s[12:13] offset:76
	global_load_dword v85, v4, s[12:13] offset:80
	global_load_dword v86, v4, s[12:13] offset:84
	global_load_dword v87, v4, s[12:13] offset:88
	global_load_dword v88, v4, s[12:13] offset:92
	global_load_dword v89, v4, s[12:13] offset:96
	global_load_dword v90, v4, s[12:13] offset:100
	global_load_dword v91, v4, s[12:13] offset:104
	global_load_dword v92, v4, s[12:13] offset:108
	global_load_dword v93, v4, s[12:13] offset:112
	global_load_dword v94, v4, s[12:13] offset:116
	global_load_dword v95, v4, s[12:13] offset:120
	global_load_dword v96, v4, s[12:13] offset:124
	global_load_dword v97, v[2:3], off
	global_load_dword v98, v[2:3], off offset:1024
	global_load_dword v99, v[2:3], off offset:2048
	global_load_dword v100, v[2:3], off offset:3072
	v_lshl_add_u64 v[2:3], v[2:3], 0, s[10:11]
	global_load_dword v101, v[2:3], off
	global_load_dword v102, v[2:3], off offset:1024
	global_load_dword v103, v[2:3], off offset:2048
	global_load_dword v104, v[2:3], off offset:3072
	v_lshl_add_u64 v[2:3], v[2:3], 0, s[10:11]
	global_load_dword v105, v[2:3], off
	global_load_dword v106, v[2:3], off offset:1024
	global_load_dword v107, v[2:3], off offset:2048
	global_load_dword v108, v[2:3], off offset:3072
	v_lshl_add_u64 v[2:3], v[2:3], 0, s[10:11]
	global_load_dword v109, v[2:3], off
	global_load_dword v110, v[2:3], off offset:1024
	global_load_dword v111, v[2:3], off offset:2048
	global_load_dword v112, v[2:3], off offset:3072
	v_lshl_add_u64 v[2:3], v[2:3], 0, s[10:11]
	global_load_dword v113, v[2:3], off
	global_load_dword v114, v[2:3], off offset:1024
	global_load_dword v115, v[2:3], off offset:2048
	global_load_dword v116, v[2:3], off offset:3072
	v_lshl_add_u64 v[2:3], v[2:3], 0, s[10:11]
	global_load_dword v117, v[2:3], off
	global_load_dword v118, v[2:3], off offset:1024
	global_load_dword v119, v[2:3], off offset:2048
	global_load_dword v120, v[2:3], off offset:3072
	v_lshl_add_u64 v[2:3], v[2:3], 0, s[10:11]
	global_load_dword v121, v[2:3], off
	global_load_dword v122, v[2:3], off offset:1024
	global_load_dword v123, v[2:3], off offset:2048
	global_load_dword v124, v[2:3], off offset:3072
	v_lshl_add_u64 v[2:3], v[2:3], 0, s[10:11]
	global_load_dword v125, v[2:3], off
	global_load_dword v126, v[2:3], off offset:1024
	global_load_dword v127, v[2:3], off offset:2048
	global_load_dword v128, v[2:3], off offset:3072
	v_lshl_add_u64 v[2:3], v[2:3], 0, s[10:11]
	s_add_i32 s18, s18, 32
	s_add_u32 s12, s12, 128
	s_addc_u32 s13, s13, 0
	s_cmp_ge_i32 s18, s9
	s_waitcnt vmcnt(31)
	v_fmac_f32_e32 v1, v65, v97
	s_waitcnt vmcnt(30)
	v_fmac_f32_e32 v1, v66, v98
	s_waitcnt vmcnt(29)
	v_fmac_f32_e32 v1, v67, v99
	s_waitcnt vmcnt(28)
	v_fmac_f32_e32 v1, v68, v100
	s_waitcnt vmcnt(27)
	v_fmac_f32_e32 v1, v69, v101
	s_waitcnt vmcnt(26)
	v_fmac_f32_e32 v1, v70, v102
	s_waitcnt vmcnt(25)
	v_fmac_f32_e32 v1, v71, v103
	s_waitcnt vmcnt(24)
	v_fmac_f32_e32 v1, v72, v104
	s_waitcnt vmcnt(23)
	v_fmac_f32_e32 v1, v73, v105
	s_waitcnt vmcnt(22)
	v_fmac_f32_e32 v1, v74, v106
	s_waitcnt vmcnt(21)
	v_fmac_f32_e32 v1, v75, v107
	s_waitcnt vmcnt(20)
	v_fmac_f32_e32 v1, v76, v108
	s_waitcnt vmcnt(19)
	v_fmac_f32_e32 v1, v77, v109
	s_waitcnt vmcnt(18)
	v_fmac_f32_e32 v1, v78, v110
	s_waitcnt vmcnt(17)
	v_fmac_f32_e32 v1, v79, v111
	s_waitcnt vmcnt(16)
	v_fmac_f32_e32 v1, v80, v112
	s_waitcnt vmcnt(15)
	v_fmac_f32_e32 v1, v81, v113
	s_waitcnt vmcnt(14)
	v_fmac_f32_e32 v1, v82, v114
	s_waitcnt vmcnt(13)
	v_fmac_f32_e32 v1, v83, v115
	s_waitcnt vmcnt(12)
	v_fmac_f32_e32 v1, v84, v116
	s_waitcnt vmcnt(11)
	v_fmac_f32_e32 v1, v85, v117
	s_waitcnt vmcnt(10)
	v_fmac_f32_e32 v1, v86, v118
	s_waitcnt vmcnt(9)
	v_fmac_f32_e32 v1, v87, v119
	s_waitcnt vmcnt(8)
	v_fmac_f32_e32 v1, v88, v120
	s_waitcnt vmcnt(7)
	v_fmac_f32_e32 v1, v89, v121
	s_waitcnt vmcnt(6)
	v_fmac_f32_e32 v1, v90, v122
	s_waitcnt vmcnt(5)
	v_fmac_f32_e32 v1, v91, v123
	s_waitcnt vmcnt(4)
	v_fmac_f32_e32 v1, v92, v124
	s_waitcnt vmcnt(3)
	v_fmac_f32_e32 v1, v93, v125
	s_waitcnt vmcnt(2)
	v_fmac_f32_e32 v1, v94, v126
	s_waitcnt vmcnt(1)
	v_fmac_f32_e32 v1, v95, v127
	s_waitcnt vmcnt(0)
	v_fmac_f32_e32 v1, v96, v128
	s_cbranch_scc0 .LBB0_133
	v_lshl_add_u32 v2, s15, 8, v0
	v_ashrrev_i32_e32 v3, 31, v2
	s_add_i32 s15, s15, s14
	s_add_i32 s16, s16, s17
	s_add_i32 s8, s8, s17
	v_lshl_add_u64 v[2:3], v[2:3], 2, s[6:7]
	s_cmp_gt_i32 s15, 15
	global_store_dword v[2:3], v1, off
	s_cbranch_scc0 .LBB0_132

.LBB0_138:
	global_load_dword v65, v4, s[12:13]
	global_load_dword v66, v4, s[12:13] offset:4
	global_load_dword v67, v4, s[12:13] offset:8
	global_load_dword v68, v4, s[12:13] offset:12
	global_load_dword v69, v4, s[12:13] offset:16
	global_load_dword v70, v4, s[12:13] offset:20
	global_load_dword v71, v4, s[12:13] offset:24
	global_load_dword v72, v4, s[12:13] offset:28
	global_load_dword v73, v4, s[12:13] offset:32
	global_load_dword v74, v4, s[12:13] offset:36
	global_load_dword v75, v4, s[12:13] offset:40
	global_load_dword v76, v4, s[12:13] offset:44
	global_load_dword v77, v4, s[12:13] offset:48
	global_load_dword v78, v4, s[12:13] offset:52
	global_load_dword v79, v4, s[12:13] offset:56
	global_load_dword v80, v4, s[12:13] offset:60
	global_load_dword v81, v4, s[12:13] offset:64
	global_load_dword v82, v4, s[12:13] offset:68
	global_load_dword v83, v4, s[12:13] offset:72
	global_load_dword v84, v4, s[12:13] offset:76
	global_load_dword v85, v4, s[12:13] offset:80
	global_load_dword v86, v4, s[12:13] offset:84
	global_load_dword v87, v4, s[12:13] offset:88
	global_load_dword v88, v4, s[12:13] offset:92
	global_load_dword v89, v4, s[12:13] offset:96
	global_load_dword v90, v4, s[12:13] offset:100
	global_load_dword v91, v4, s[12:13] offset:104
	global_load_dword v92, v4, s[12:13] offset:108
	global_load_dword v93, v4, s[12:13] offset:112
	global_load_dword v94, v4, s[12:13] offset:116
	global_load_dword v95, v4, s[12:13] offset:120
	global_load_dword v96, v4, s[12:13] offset:124
	global_load_dword v97, v[2:3], off
	global_load_dword v98, v[2:3], off offset:1024
	global_load_dword v99, v[2:3], off offset:2048
	global_load_dword v100, v[2:3], off offset:3072
	v_lshl_add_u64 v[2:3], v[2:3], 0, s[10:11]
	global_load_dword v101, v[2:3], off
	global_load_dword v102, v[2:3], off offset:1024
	global_load_dword v103, v[2:3], off offset:2048
	global_load_dword v104, v[2:3], off offset:3072
	v_lshl_add_u64 v[2:3], v[2:3], 0, s[10:11]
	global_load_dword v105, v[2:3], off
	global_load_dword v106, v[2:3], off offset:1024
	global_load_dword v107, v[2:3], off offset:2048
	global_load_dword v108, v[2:3], off offset:3072
	v_lshl_add_u64 v[2:3], v[2:3], 0, s[10:11]
	global_load_dword v109, v[2:3], off
	global_load_dword v110, v[2:3], off offset:1024
	global_load_dword v111, v[2:3], off offset:2048
	global_load_dword v112, v[2:3], off offset:3072
	v_lshl_add_u64 v[2:3], v[2:3], 0, s[10:11]
	global_load_dword v113, v[2:3], off
	global_load_dword v114, v[2:3], off offset:1024
	global_load_dword v115, v[2:3], off offset:2048
	global_load_dword v116, v[2:3], off offset:3072
	v_lshl_add_u64 v[2:3], v[2:3], 0, s[10:11]
	global_load_dword v117, v[2:3], off
	global_load_dword v118, v[2:3], off offset:1024
	global_load_dword v119, v[2:3], off offset:2048
	global_load_dword v120, v[2:3], off offset:3072
	v_lshl_add_u64 v[2:3], v[2:3], 0, s[10:11]
	global_load_dword v121, v[2:3], off
	global_load_dword v122, v[2:3], off offset:1024
	global_load_dword v123, v[2:3], off offset:2048
	global_load_dword v124, v[2:3], off offset:3072
	v_lshl_add_u64 v[2:3], v[2:3], 0, s[10:11]
	global_load_dword v125, v[2:3], off
	global_load_dword v126, v[2:3], off offset:1024
	global_load_dword v127, v[2:3], off offset:2048
	global_load_dword v128, v[2:3], off offset:3072
	v_lshl_add_u64 v[2:3], v[2:3], 0, s[10:11]
	s_add_i32 s18, s18, 32
	s_add_u32 s12, s12, 128
	s_addc_u32 s13, s13, 0
	s_cmp_ge_i32 s18, s9
	s_waitcnt vmcnt(31)
	v_fmac_f32_e32 v1, v65, v97
	s_waitcnt vmcnt(30)
	v_fmac_f32_e32 v1, v66, v98
	s_waitcnt vmcnt(29)
	v_fmac_f32_e32 v1, v67, v99
	s_waitcnt vmcnt(28)
	v_fmac_f32_e32 v1, v68, v100
	s_waitcnt vmcnt(27)
	v_fmac_f32_e32 v1, v69, v101
	s_waitcnt vmcnt(26)
	v_fmac_f32_e32 v1, v70, v102
	s_waitcnt vmcnt(25)
	v_fmac_f32_e32 v1, v71, v103
	s_waitcnt vmcnt(24)
	v_fmac_f32_e32 v1, v72, v104
	s_waitcnt vmcnt(23)
	v_fmac_f32_e32 v1, v73, v105
	s_waitcnt vmcnt(22)
	v_fmac_f32_e32 v1, v74, v106
	s_waitcnt vmcnt(21)
	v_fmac_f32_e32 v1, v75, v107
	s_waitcnt vmcnt(20)
	v_fmac_f32_e32 v1, v76, v108
	s_waitcnt vmcnt(19)
	v_fmac_f32_e32 v1, v77, v109
	s_waitcnt vmcnt(18)
	v_fmac_f32_e32 v1, v78, v110
	s_waitcnt vmcnt(17)
	v_fmac_f32_e32 v1, v79, v111
	s_waitcnt vmcnt(16)
	v_fmac_f32_e32 v1, v80, v112
	s_waitcnt vmcnt(15)
	v_fmac_f32_e32 v1, v81, v113
	s_waitcnt vmcnt(14)
	v_fmac_f32_e32 v1, v82, v114
	s_waitcnt vmcnt(13)
	v_fmac_f32_e32 v1, v83, v115
	s_waitcnt vmcnt(12)
	v_fmac_f32_e32 v1, v84, v116
	s_waitcnt vmcnt(11)
	v_fmac_f32_e32 v1, v85, v117
	s_waitcnt vmcnt(10)
	v_fmac_f32_e32 v1, v86, v118
	s_waitcnt vmcnt(9)
	v_fmac_f32_e32 v1, v87, v119
	s_waitcnt vmcnt(8)
	v_fmac_f32_e32 v1, v88, v120
	s_waitcnt vmcnt(7)
	v_fmac_f32_e32 v1, v89, v121
	s_waitcnt vmcnt(6)
	v_fmac_f32_e32 v1, v90, v122
	s_waitcnt vmcnt(5)
	v_fmac_f32_e32 v1, v91, v123
	s_waitcnt vmcnt(4)
	v_fmac_f32_e32 v1, v92, v124
	s_waitcnt vmcnt(3)
	v_fmac_f32_e32 v1, v93, v125
	s_waitcnt vmcnt(2)
	v_fmac_f32_e32 v1, v94, v126
	s_waitcnt vmcnt(1)
	v_fmac_f32_e32 v1, v95, v127
	s_waitcnt vmcnt(0)
	v_fmac_f32_e32 v1, v96, v128
	s_cbranch_scc0 .LBB0_138
	s_lshl_b32 s9, s15, 8
	s_addk_i32 s9, 0x1000
	v_add_u32_e32 v2, s9, v0
	v_ashrrev_i32_e32 v3, 31, v2
	s_add_i32 s15, s15, s14
	s_add_i32 s16, s16, s17
	s_add_i32 s8, s8, s17
	v_lshl_add_u64 v[2:3], v[2:3], 2, s[6:7]
	s_cmp_gt_i32 s15, 15
	global_store_dword v[2:3], v1, off
	s_cbranch_scc0 .LBB0_137
